# phase2_state_stores_nt
# baseline (speedup 1.0000x reference)
.LBB0_469:
	s_or_b64 exec, exec, s[8:9]
	v_or_b32_e32 v0, s47, v129
	v_mul_lo_u32 v0, v0, s75
	v_lshlrev_b32_e32 v8, 4, v130
	v_mul_u32_u24_e32 v9, 0x90, v129
	v_add3_u32 v4, 0, v0, v8
	v_add3_u32 v68, 0, v9, v8
	s_waitcnt lgkmcnt(0)
	s_barrier
	ds_read_b128 v[0:3], v4
	ds_read_b128 v[4:7], v4 offset:64
	ds_read_b128 v[8:11], v68 offset:18432
	ds_read_b128 v[12:15], v68 offset:18496
	ds_read_b128 v[16:19], v68 offset:20736
	ds_read_b128 v[20:23], v68 offset:20800
	ds_read_b128 v[24:27], v68 offset:23040
	ds_read_b128 v[28:31], v68 offset:23104
	ds_read_b128 v[32:35], v68 offset:25344
	ds_read_b128 v[36:39], v68 offset:25408
	ds_read_b128 v[40:43], v68 offset:27648
	ds_read_b128 v[44:47], v68 offset:27712
	ds_read_b128 v[48:51], v68 offset:29952
	ds_read_b128 v[52:55], v68 offset:30016
	ds_read_b128 v[56:59], v68 offset:32256
	ds_read_b128 v[60:63], v68 offset:32320
	ds_read_b128 v[64:67], v68 offset:34560
	ds_read_b128 v[68:71], v68 offset:34624
	s_ashr_i32 s55, s54, 31
	s_lshl_b64 s[0:1], s[52:53], 17
	s_lshl_b64 s[4:5], s[54:55], 15
	s_add_u32 s0, s16, s0
	s_addc_u32 s1, s17, s1
	s_add_u32 s0, s0, s4
	v_lshlrev_b32_e32 v84, 3, v130
	s_addc_u32 s1, s1, s5
	s_waitcnt lgkmcnt(14)
	v_mfma_f32_16x16x32_bf16 v[8:11], v[0:3], v[8:11], 0
	s_lshl_b32 s4, s47, 1
	s_add_u32 s0, s0, s4
	s_addc_u32 s1, s1, 0
	v_mfma_f32_16x16x32_bf16 v[8:11], v[4:7], v[12:15], v[8:11]
	s_waitcnt lgkmcnt(13)
	v_mfma_f32_16x16x32_bf16 v[12:15], v[0:3], v[16:19], 0
	s_waitcnt lgkmcnt(11)
	v_mfma_f32_16x16x32_bf16 v[16:19], v[0:3], v[24:27], 0
	v_mfma_f32_16x16x32_bf16 v[12:15], v[4:7], v[20:23], v[12:15]
	s_nop 2
	v_cvt_pk_bf16_f32 v22, v8, v9
	v_cvt_pk_bf16_f32 v23, v10, v11
	v_lshl_add_u64 v[20:21], s[0:1], 0, v[84:85]
	s_waitcnt lgkmcnt(10)
	v_mfma_f32_16x16x32_bf16 v[8:11], v[4:7], v[28:31], v[16:19]
	v_lshlrev_b32_e32 v84, 8, v129
	v_lshl_add_u64 v[20:21], v[20:21], 0, v[84:85]
	global_store_dwordx2 v[20:21], v[22:23], off nt
	v_cvt_pk_bf16_f32 v16, v12, v13
	v_cvt_pk_bf16_f32 v17, v14, v15
	s_waitcnt lgkmcnt(9)
	v_mfma_f32_16x16x32_bf16 v[12:15], v[0:3], v[32:35], 0
	v_add_co_u32_e32 v18, vcc, s69, v20
	v_cvt_pk_bf16_f32 v8, v8, v9
	s_nop 0
	v_addc_co_u32_e32 v19, vcc, 0, v21, vcc
	v_cvt_pk_bf16_f32 v9, v10, v11
	s_waitcnt lgkmcnt(8)
	v_mfma_f32_16x16x32_bf16 v[12:15], v[4:7], v[36:39], v[12:15]
	global_store_dwordx2 v[18:19], v[8:9], off nt
	global_store_dwordx2 v[18:19], v[16:17], off offset:-4096 nt
	v_add_co_u32_e32 v16, vcc, s83, v20
	s_waitcnt lgkmcnt(7)
	v_mfma_f32_16x16x32_bf16 v[8:11], v[0:3], v[40:43], 0
	s_nop 2
	v_cvt_pk_bf16_f32 v12, v12, v13
	v_cvt_pk_bf16_f32 v13, v14, v15
	v_addc_co_u32_e32 v17, vcc, 0, v21, vcc
	s_waitcnt lgkmcnt(6)
	v_mfma_f32_16x16x32_bf16 v[8:11], v[4:7], v[44:47], v[8:11]
	global_store_dwordx2 v[16:17], v[12:13], off offset:-4096 nt
	s_waitcnt lgkmcnt(5)
	v_mfma_f32_16x16x32_bf16 v[12:15], v[0:3], v[48:51], 0
	s_nop 4
	v_cvt_pk_bf16_f32 v8, v8, v9
	v_cvt_pk_bf16_f32 v9, v10, v11
	global_store_dwordx2 v[16:17], v[8:9], off nt
	s_waitcnt lgkmcnt(4)
	v_mfma_f32_16x16x32_bf16 v[8:11], v[4:7], v[52:55], v[12:15]
	s_nop 2
	v_add_co_u32_e32 v14, vcc, s66, v20
	s_nop 1
	v_addc_co_u32_e32 v15, vcc, 0, v21, vcc
	s_nop 0
	v_cvt_pk_bf16_f32 v12, v8, v9
	v_cvt_pk_bf16_f32 v13, v10, v11
	s_waitcnt lgkmcnt(3)
	v_mfma_f32_16x16x32_bf16 v[8:11], v[0:3], v[56:59], 0
	global_store_dwordx2 v[14:15], v[12:13], off nt
	s_waitcnt lgkmcnt(1)
	v_mfma_f32_16x16x32_bf16 v[0:3], v[0:3], v[64:67], 0
	v_mfma_f32_16x16x32_bf16 v[8:11], v[4:7], v[60:63], v[8:11]
	s_waitcnt lgkmcnt(0)
	v_mfma_f32_16x16x32_bf16 v[0:3], v[4:7], v[68:71], v[0:3]
	s_nop 5
	v_cvt_pk_bf16_f32 v8, v8, v9
	v_cvt_pk_bf16_f32 v9, v10, v11
	v_add_co_u32_e32 v10, vcc, 0x6000, v20
	v_cvt_pk_bf16_f32 v0, v0, v1
	s_nop 0
	v_addc_co_u32_e32 v11, vcc, 0, v21, vcc
	v_cvt_pk_bf16_f32 v1, v2, v3
	v_add_co_u32_e32 v2, vcc, 0x7000, v20
	global_store_dwordx2 v[10:11], v[8:9], off nt
	s_nop 0
	v_addc_co_u32_e32 v3, vcc, 0, v21, vcc
	global_store_dwordx2 v[2:3], v[0:1], off nt
	s_barrier

.LBB0_514:
	ds_read_b128 v[12:15], v10
	ds_read_b128 v[16:19], v10 offset:64
	ds_read_b128 v[20:23], v10 offset:2304
	ds_read_b128 v[24:27], v10 offset:2368
	ds_read_b128 v[28:31], v10 offset:4608
	ds_read_b128 v[32:35], v10 offset:4672
	ds_read_b128 v[36:39], v10 offset:6912
	ds_read_b128 v[40:43], v10 offset:6976
	s_waitcnt lgkmcnt(7)
	v_mfma_f32_16x16x32_bf16 v[12:15], v[0:3], v[12:15], 0
	v_lshl_add_u64 v[44:45], v[8:9], 0, s[4:5]
	s_add_u32 s4, s4, 0x4000
	v_add_co_u32_e32 v46, vcc, s77, v44
	s_waitcnt lgkmcnt(5)
	v_mfma_f32_16x16x32_bf16 v[20:23], v[0:3], v[20:23], 0
	v_addc_co_u32_e32 v47, vcc, 0, v45, vcc
	s_addc_u32 s5, s5, 0
	s_waitcnt lgkmcnt(3)
	v_mfma_f32_16x16x32_bf16 v[28:31], v[0:3], v[28:31], 0
	v_add_u32_e32 v10, 0x2400, v10
	v_add_co_u32_e32 v44, vcc, s79, v44
	s_waitcnt lgkmcnt(1)
	v_mfma_f32_16x16x32_bf16 v[36:39], v[0:3], v[36:39], 0
	s_cmp_eq_u32 s4, 0x10000
	v_addc_co_u32_e32 v45, vcc, 0, v45, vcc
	v_mfma_f32_16x16x32_bf16 v[12:15], v[4:7], v[16:19], v[12:15]
	v_mfma_f32_16x16x32_bf16 v[16:19], v[4:7], v[24:27], v[20:23]
	v_mfma_f32_16x16x32_bf16 v[20:23], v[4:7], v[32:35], v[28:31]
	s_nop 5
	v_cvt_pk_bf16_f32 v12, v12, v13
	v_cvt_pk_bf16_f32 v13, v14, v15
	v_cvt_pk_bf16_f32 v14, v16, v17
	s_waitcnt lgkmcnt(0)
	v_mfma_f32_16x16x32_bf16 v[24:27], v[4:7], v[40:43], v[36:39]
	v_cvt_pk_bf16_f32 v15, v18, v19
	v_cvt_pk_bf16_f32 v16, v20, v21
	v_cvt_pk_bf16_f32 v17, v22, v23
	s_nop 4
	v_cvt_pk_bf16_f32 v18, v24, v25
	v_cvt_pk_bf16_f32 v19, v26, v27
	global_store_dwordx2 v[46:47], v[12:13], off offset:-4096 nt
	global_store_dwordx2 v[46:47], v[14:15], off nt
	global_store_dwordx2 v[44:45], v[16:17], off offset:-4096 nt
	global_store_dwordx2 v[44:45], v[18:19], off nt
	s_cbranch_scc0 .LBB0_514
	s_barrier
	s_branch .LBB0_470
